# P8: final pair-combination top-16 step moved from wave 0 (which also scans and merges) to wave 3, balancing VALU work across the workgroup's waves
# baseline (speedup 1.0000x reference)
; DI void phase8(const Params& p, char* smem) {
;   const u16* PQ = (const u16*)(p.ws + WS_P); const u16* SK = (const u16*)(p.ws + WS_SK);
;   int* IDS = (int*)(p.ws + WS_IDS); float* GATE = (float*)(p.ws + WS_GATE);
;   float* sc = (float*)(smem + 16);
;   const int tid = threadIdx.x, lane = tid & 63, w = tid >> 6, r = lane & 31, hi = lane >> 5;
;   for (int it = blockIdx.x; it < 128 * 8; it += gridDim.x) {
;     const int h = it & 7, tile = it >> 3;
;     const int pp = w >> 1, rh = w & 1;
;     ...
;     if (tid < 64) {
;       const float* ra = sc + tid * 129; const float* rb = sc + (64 + tid) * 129;
.LBB0_1048:
	s_cmpk_gt_i32 s12, 0x3ff
	s_cbranch_scc1 .LBB0_1059
	v_bfe_u32 v3, v0, 5, 1
	v_mov_b32_e32 v67, 0
	v_lshlrev_b32_e32 v66, 4, v3
	s_add_u32 s8, s82, 0x8538000
	v_lshrrev_b32_e32 v8, 1, v0
	v_lshl_add_u64 v[6:7], s[82:83], 0, v[66:67]
	s_mov_b64 s[2:3], 0x24b8000
	s_addc_u32 s9, s83, 0
	v_and_b32_e32 v9, 32, v8
	v_lshlrev_b32_e32 v4, 3, v3
	v_lshl_add_u64 v[68:69], v[6:7], 0, s[2:3]
	v_and_b32_e32 v6, 0x1c0, v8
	v_lshlrev_b32_e32 v3, 2, v3
	s_add_u32 s10, s82, 0x16638000
	v_and_b32_e32 v5, 31, v0
	s_load_dword s20, s[0:1], 0xc0
	v_or3_b32 v3, v3, v6, v9
	s_addc_u32 s11, s83, 0
	v_or_b32_e32 v1, v9, v5
	v_lshlrev_b32_e32 v5, 2, v5
	v_lshrrev_b32_e32 v8, 7, v0
	v_mul_u32_u24_e32 v3, 0x204, v3
	s_add_u32 s14, s82, 0x16a38000
	v_and_b32_e32 v7, 0x7f, v0
	s_waitcnt lgkmcnt(0)
	s_movk_i32 s16, 0x204
	v_add3_u32 v79, 0, v5, v3
	v_lshlrev_b32_e32 v3, 8, v8
	s_addc_u32 s15, s83, 0
	v_and_b32_e32 v2, 0x380, v0
	v_lshlrev_b32_e32 v10, 6, v8
	s_add_i32 s6, 0, 0x10210
	s_movk_i32 s4, 0x80
	v_mad_u32_u24 v3, v7, s16, v3
	v_and_b32_e32 v74, 0x39f, v0
	s_mov_b32 s17, 0
	s_movk_i32 s13, 0x7f
	v_mad_u32_u24 v75, v7, s16, 0
	v_cmp_eq_u32_e64 s[2:3], 1, v8
	v_lshl_add_u32 v76, v7, 2, s6
	v_cmp_gt_u32_e64 s[4:5], s4, v0
	v_lshl_add_u32 v77, v0, 2, s6
	v_lshrrev_b32_e32 v78, 6, v0
	v_cmp_eq_u32_e64 s[6:7], 3, v78
	v_subrev_u32_e32 v78, 0xc0, v0
	v_mad_u32_u24 v78, v78, s16, 0
	v_sub_u32_e32 v80, 0x7c, v10
	v_add3_u32 v81, v3, 0, 16
	v_lshlrev_b32_e32 v70, 1, v2
	v_mov_b32_e32 v71, v67
	v_lshlrev_b32_e32 v72, 1, v4
	v_mov_b32_e32 v73, v67
	s_movk_i32 s21, 0x2000
	s_movk_i32 s22, 0x4000
	s_movk_i32 s23, 0x6000
	s_brev_b32 s24, 1
	s_movk_i32 s25, 0xff80
	s_movk_i32 s26, 0xff
	s_movk_i32 s27, 0xff00
	s_mov_b32 s28, 0xf149f2ca
	s_waitcnt vmcnt(6)
	v_add_u32_e32 v82, 0x400, v79
	v_add_u32_e32 v83, 0x1000, v79
	v_add_u32_e32 v84, 0x1400, v79
	v_add_u32_e32 v85, 0x2000, v79
	v_add_u32_e32 v86, 0x2400, v79
	v_add_u32_e32 v87, 0x3000, v79
	v_add_u32_e32 v88, 0x3400, v79
	s_mov_b32 s29, s12
	s_branch .LBB0_1051

; DI unsigned f2ord(float v) { unsigned u = __float_as_uint(v); return u ^ ((unsigned)((int)u >> 31) | 0x80000000u); }
; #define TOPK_INSERT(keys, x) { _Pragma("unroll") for (int _j = 15; _j >= 1; --_j) keys[_j] = med3u(keys[_j - 1], keys[_j], x); keys[0] = max(keys[0], x); }
; DI void phase8(const Params& p, char* smem) {
;     ...
;     if (tid < 64) {
;       const float* ra = sc + tid * 129; const float* rb = sc + (64 + tid) * 129;
;       float a[16], bq[16];
; #pragma unroll
;       for (int j = 0; j < 16; ++j) { a[j] = ra[j]; bq[j] = rb[j]; }
;       unsigned keys[16];
; #pragma unroll
;       for (int j = 0; j < 16; ++j) keys[j] = 0u;
; #pragma unroll
;       for (int i = 0; i < 16; ++i)
; #pragma unroll
;         for (int j = 0; j < 16; ++j)
;           if ((i + 1) * (j + 1) <= 16) {
;             unsigned x = (f2ord(a[i] + bq[j]) & 0xFFFFFF00u) | (unsigned)(255 - (i * 16 + j));
;             TOPK_INSERT(keys, x);
.LBB0_1057:
	s_or_b64 exec, exec, s[18:19]
	s_waitcnt lgkmcnt(0)
	s_barrier
	s_and_saveexec_b64 s[18:19], s[6:7]
	s_cbranch_execz .LBB0_1050
	ds_read2_b32 v[10:11], v78 offset0:12 offset1:13
	ds_read2_b32 v[8:9], v78 offset0:14 offset1:15
	ds_read2_b32 v[6:7], v78 offset0:16 offset1:17
	ds_read2_b32 v[2:3], v78 offset0:18 offset1:19
	ds_read2_b32 v[16:17], v78 offset0:4 offset1:5
	v_add_u32_e32 v4, 0x8110, v78
	v_add_u32_e32 v12, 0x8118, v78
	v_add_u32_e32 v13, 0x8120, v78
	v_add_u32_e32 v20, 0x8128, v78
	ds_read2_b32 v[4:5], v4 offset1:1
	ds_read2_b32 v[14:15], v12 offset1:1
	ds_read2_b32 v[18:19], v13 offset1:1
	ds_read2_b32 v[20:21], v20 offset1:1
	ds_read2_b32 v[12:13], v78 offset0:10 offset1:11
	ds_read2_b32 v[34:35], v78 offset0:6 offset1:7
	ds_read2_b32 v[38:39], v78 offset0:8 offset1:9
	s_waitcnt lgkmcnt(6)
	v_add_f32_e32 v22, v16, v4
	v_ashrrev_i32_e32 v23, 31, v22
	v_or_b32_e32 v23, 0x80000000, v23
	v_bitop3_b32 v44, v23, s26, v22 bitop3:0xde
	v_add_f32_e32 v22, v16, v5
	v_ashrrev_i32_e32 v23, 31, v22
	v_or_b32_e32 v23, 0x80000000, v23
	v_bitop3_b32 v22, v23, s27, v22 bitop3:0x48
	s_waitcnt lgkmcnt(5)
	v_add_f32_e32 v23, v16, v14
	v_ashrrev_i32_e32 v24, 31, v23
	v_or_b32_e32 v24, 0x80000000, v24
	v_or_b32_e32 v46, 0xfe, v22
	v_bitop3_b32 v23, v24, s27, v23 bitop3:0x48
	v_max_u32_e32 v22, v44, v46
	v_or_b32_e32 v49, 0xfd, v23
	v_max_u32_e32 v50, v22, v49
	v_add_f32_e32 v22, v16, v15
	v_ashrrev_i32_e32 v23, 31, v22
	v_or_b32_e32 v23, 0x80000000, v23
	v_bitop3_b32 v22, v23, s27, v22 bitop3:0x48
	v_or_b32_e32 v51, 0xfc, v22
	s_waitcnt lgkmcnt(4)
	v_add_f32_e32 v22, v16, v18
	v_ashrrev_i32_e32 v23, 31, v22
	v_or_b32_e32 v23, 0x80000000, v23
	v_bitop3_b32 v22, v23, s27, v22 bitop3:0x48
	v_or_b32_e32 v53, 0xfb, v22
	v_add_f32_e32 v22, v16, v19
	v_ashrrev_i32_e32 v23, 31, v22
	v_or_b32_e32 v23, 0x80000000, v23
	v_bitop3_b32 v22, v23, s27, v22 bitop3:0x48
	v_or_b32_e32 v55, 0xfa, v22
	s_waitcnt lgkmcnt(3)
	v_add_f32_e32 v22, v16, v20
	v_ashrrev_i32_e32 v23, 31, v22
	v_or_b32_e32 v23, 0x80000000, v23
	v_bitop3_b32 v22, v23, s27, v22 bitop3:0x48
	v_or_b32_e32 v57, 0xf9, v22
	v_add_f32_e32 v22, v16, v21
	v_ashrrev_i32_e32 v23, 31, v22
	v_or_b32_e32 v23, 0x80000000, v23
	v_bitop3_b32 v22, v23, s27, v22 bitop3:0x48
	v_or_b32_e32 v48, 0xf8, v22
	v_add_u32_e32 v22, 0x8130, v78
	ds_read2_b32 v[22:23], v22 offset1:1
	v_add_u32_e32 v24, 0x8138, v78
	v_add_u32_e32 v26, 0x8140, v78
	v_add_u32_e32 v28, 0x8148, v78
	ds_read2_b32 v[24:25], v24 offset1:1
	ds_read2_b32 v[26:27], v26 offset1:1
	ds_read2_b32 v[28:29], v28 offset1:1
	s_waitcnt lgkmcnt(3)
	v_add_f32_e32 v22, v16, v22
	v_ashrrev_i32_e32 v30, 31, v22
	v_or_b32_e32 v30, 0x80000000, v30
	v_bitop3_b32 v22, v30, s27, v22 bitop3:0x48
	v_or_b32_e32 v47, 0xf7, v22
	v_add_f32_e32 v22, v16, v23
	v_ashrrev_i32_e32 v23, 31, v22
	v_or_b32_e32 v23, 0x80000000, v23
	v_bitop3_b32 v22, v23, s27, v22 bitop3:0x48
	v_or_b32_e32 v45, 0xf6, v22
	s_waitcnt lgkmcnt(2)
	v_add_f32_e32 v22, v16, v24
	v_ashrrev_i32_e32 v23, 31, v22
	v_or_b32_e32 v23, 0x80000000, v23
	v_bitop3_b32 v22, v23, s27, v22 bitop3:0x48
	v_or_b32_e32 v43, 0xf5, v22
	v_add_f32_e32 v22, v16, v25
	v_ashrrev_i32_e32 v23, 31, v22
	v_or_b32_e32 v23, 0x80000000, v23
	v_bitop3_b32 v22, v23, s27, v22 bitop3:0x48
	v_or_b32_e32 v42, 0xf4, v22
	s_waitcnt lgkmcnt(1)
	v_add_f32_e32 v22, v16, v26
	v_ashrrev_i32_e32 v23, 31, v22
	v_or_b32_e32 v23, 0x80000000, v23
	v_bitop3_b32 v22, v23, s27, v22 bitop3:0x48
	v_or_b32_e32 v37, 0xf3, v22
	v_add_f32_e32 v22, v16, v27
	v_ashrrev_i32_e32 v23, 31, v22
	v_or_b32_e32 v23, 0x80000000, v23
	v_bitop3_b32 v22, v23, s27, v22 bitop3:0x48
	v_or_b32_e32 v31, 0xf2, v22
	s_waitcnt lgkmcnt(0)
	v_add_f32_e32 v22, v16, v28
	v_ashrrev_i32_e32 v23, 31, v22
	v_or_b32_e32 v23, 0x80000000, v23
	v_bitop3_b32 v22, v23, s27, v22 bitop3:0x48
	v_add_f32_e32 v16, v16, v29
	v_or_b32_e32 v27, 0xf1, v22
	v_ashrrev_i32_e32 v22, 31, v16
	v_or_b32_e32 v22, 0x80000000, v22
	v_bitop3_b32 v16, v22, s27, v16 bitop3:0x48
	v_add_f32_e32 v22, v4, v17
	v_ashrrev_i32_e32 v23, 31, v22
	v_or_b32_e32 v23, 0x80000000, v23
	v_bitop3_b32 v22, v23, s27, v22 bitop3:0x48
	v_add_f32_e32 v23, v17, v5
	v_ashrrev_i32_e32 v24, 31, v23
	v_or_b32_e32 v24, 0x80000000, v24
	v_bitop3_b32 v23, v24, s27, v23 bitop3:0x48
	v_add_f32_e32 v24, v17, v14
	v_ashrrev_i32_e32 v25, 31, v24
	v_or_b32_e32 v25, 0x80000000, v25
	v_bitop3_b32 v24, v25, s27, v24 bitop3:0x48
	v_add_f32_e32 v25, v17, v15
	v_ashrrev_i32_e32 v26, 31, v25
	v_or_b32_e32 v26, 0x80000000, v26
	v_bitop3_b32 v25, v26, s27, v25 bitop3:0x48
	v_add_f32_e32 v26, v17, v18
	v_ashrrev_i32_e32 v28, 31, v26
	v_or_b32_e32 v28, 0x80000000, v28
	v_add_f32_e32 v19, v17, v19
	v_bitop3_b32 v26, v28, s27, v26 bitop3:0x48
	v_ashrrev_i32_e32 v28, 31, v19
	v_add_f32_e32 v20, v17, v20
	v_add_f32_e32 v17, v17, v21
	v_or_b32_e32 v28, 0x80000000, v28
	v_ashrrev_i32_e32 v21, 31, v17
	v_bitop3_b32 v19, v28, s27, v19 bitop3:0x48
	v_ashrrev_i32_e32 v28, 31, v20
	v_or_b32_e32 v21, 0x80000000, v21
	v_or_b32_e32 v28, 0x80000000, v28
	v_bitop3_b32 v17, v21, s27, v17 bitop3:0x48
	v_add_f32_e32 v21, v4, v34
	v_bitop3_b32 v20, v28, s27, v20 bitop3:0x48
	v_ashrrev_i32_e32 v28, 31, v21
	v_or_b32_e32 v28, 0x80000000, v28
	v_bitop3_b32 v21, v28, s27, v21 bitop3:0x48
	v_add_f32_e32 v28, v5, v34
	v_ashrrev_i32_e32 v29, 31, v28
	v_or_b32_e32 v29, 0x80000000, v29
	v_bitop3_b32 v28, v29, s27, v28 bitop3:0x48
	v_add_f32_e32 v29, v34, v14
	v_ashrrev_i32_e32 v30, 31, v29
	v_or_b32_e32 v30, 0x80000000, v30
	v_bitop3_b32 v29, v30, s27, v29 bitop3:0x48
	v_add_f32_e32 v30, v34, v15
	v_ashrrev_i32_e32 v32, 31, v30
	v_or_b32_e32 v32, 0x80000000, v32
	v_add_f32_e32 v18, v34, v18
; #define TOPK_INSERT(keys, x) { _Pragma("unroll") for (int _j = 15; _j >= 1; --_j) keys[_j] = med3u(keys[_j - 1], keys[_j], x); keys[0] = max(keys[0], x); }
; DI unsigned f2ord(float v) { unsigned u = __float_as_uint(v); return u ^ ((unsigned)((int)u >> 31) | 0x80000000u); }
; DI void phase8(const Params& p, char* smem) {
;     ...
;       for (int i = 0; i < 16; ++i)
; #pragma unroll
;         for (int j = 0; j < 16; ++j)
;           if ((i + 1) * (j + 1) <= 16) {
;             unsigned x = (f2ord(a[i] + bq[j]) & 0xFFFFFF00u) | (unsigned)(255 - (i * 16 + j));
;             TOPK_INSERT(keys, x);
;           }
	v_bitop3_b32 v30, v32, s27, v30 bitop3:0x48
	v_ashrrev_i32_e32 v32, 31, v18
	v_or_b32_e32 v32, 0x80000000, v32
	v_bitop3_b32 v18, v32, s27, v18 bitop3:0x48
	v_add_f32_e32 v32, v4, v35
	v_ashrrev_i32_e32 v33, 31, v32
	v_min_u32_e32 v122, v44, v46
	v_med3_u32 v46, v44, v46, v49
	v_max_u32_e32 v52, v50, v51
	v_or_b32_e32 v33, 0x80000000, v33
	v_med3_u32 v50, v50, v46, v51
	v_max_u32_e32 v54, v52, v53
	v_bitop3_b32 v32, v33, s27, v32 bitop3:0x48
	v_add_f32_e32 v33, v5, v35
	v_med3_u32 v52, v52, v50, v53
	v_max_u32_e32 v56, v54, v55
	v_ashrrev_i32_e32 v34, 31, v33
	v_med3_u32 v54, v54, v52, v55
	v_max_u32_e32 v58, v56, v57
	v_or_b32_e32 v34, 0x80000000, v34
	v_add_f32_e32 v15, v35, v15
	v_med3_u32 v56, v56, v54, v57
	v_max_u32_e32 v59, v58, v48
	v_bitop3_b32 v33, v34, s27, v33 bitop3:0x48
	v_add_f32_e32 v34, v14, v35
	v_ashrrev_i32_e32 v35, 31, v15
	v_med3_u32 v58, v58, v56, v48
	v_max_u32_e32 v60, v59, v47
	v_ashrrev_i32_e32 v36, 31, v34
	v_or_b32_e32 v35, 0x80000000, v35
	v_med3_u32 v59, v59, v58, v47
	v_max_u32_e32 v61, v60, v45
	v_or_b32_e32 v36, 0x80000000, v36
	v_bitop3_b32 v15, v35, s27, v15 bitop3:0x48
	v_add_f32_e32 v35, v4, v38
	v_med3_u32 v60, v60, v59, v45
	v_max_u32_e32 v62, v61, v43
	v_bitop3_b32 v34, v36, s27, v34 bitop3:0x48
	v_ashrrev_i32_e32 v36, 31, v35
	v_med3_u32 v61, v61, v60, v43
	v_max_u32_e32 v63, v62, v42
	v_or_b32_e32 v36, 0x80000000, v36
	v_add_f32_e32 v14, v14, v38
	v_med3_u32 v62, v62, v61, v42
	v_max_u32_e32 v64, v63, v37
	v_bitop3_b32 v35, v36, s27, v35 bitop3:0x48
	v_add_f32_e32 v36, v5, v38
	v_ashrrev_i32_e32 v38, 31, v14
	v_med3_u32 v63, v63, v62, v37
	v_max_u32_e32 v65, v64, v31
	v_ashrrev_i32_e32 v40, 31, v36
	v_or_b32_e32 v38, 0x80000000, v38
	v_med3_u32 v64, v64, v63, v31
	v_max_u32_e32 v66, v65, v27
	v_or_b32_e32 v16, 0xf0, v16
	v_or_b32_e32 v40, 0x80000000, v40
	v_bitop3_b32 v14, v38, s27, v14 bitop3:0x48
	v_add_f32_e32 v38, v4, v39
	v_med3_u32 v65, v65, v64, v27
	v_max_u32_e32 v89, v66, v16
	v_or_b32_e32 v22, 0xef, v22
	v_bitop3_b32 v36, v40, s27, v36 bitop3:0x48
	v_ashrrev_i32_e32 v40, 31, v38
	v_med3_u32 v66, v66, v65, v16
	v_max_u32_e32 v90, v89, v22
	v_or_b32_e32 v23, 0xee, v23
	v_or_b32_e32 v40, 0x80000000, v40
	v_add_f32_e32 v39, v5, v39
	v_med3_u32 v89, v89, v66, v22
	v_max_u32_e32 v91, v90, v23
	v_or_b32_e32 v24, 0xed, v24
	v_bitop3_b32 v38, v40, s27, v38 bitop3:0x48
	v_ashrrev_i32_e32 v40, 31, v39
	v_med3_u32 v90, v90, v89, v23
	v_max_u32_e32 v92, v91, v24
	v_or_b32_e32 v25, 0xec, v25
	v_or_b32_e32 v40, 0x80000000, v40
	v_med3_u32 v91, v91, v90, v24
	v_max_u32_e32 v93, v92, v25
	v_or_b32_e32 v26, 0xeb, v26
	v_bitop3_b32 v39, v40, s27, v39 bitop3:0x48
	v_add_f32_e32 v40, v4, v12
	v_med3_u32 v92, v92, v91, v25
	v_max_u32_e32 v94, v93, v26
	v_or_b32_e32 v19, 0xea, v19
	v_ashrrev_i32_e32 v41, 31, v40
	v_med3_u32 v93, v93, v92, v26
	v_max_u32_e32 v95, v94, v19
	v_or_b32_e32 v20, 0xe9, v20
	v_or_b32_e32 v41, 0x80000000, v41
	v_add_f32_e32 v12, v5, v12
	v_med3_u32 v94, v94, v93, v19
	v_max_u32_e32 v96, v95, v20
	v_or_b32_e32 v17, 0xe8, v17
	v_bitop3_b32 v40, v41, s27, v40 bitop3:0x48
	v_ashrrev_i32_e32 v41, 31, v12
	v_med3_u32 v95, v95, v94, v20
	v_max_u32_e32 v97, v96, v17
	v_or_b32_e32 v21, 0xdf, v21
	v_or_b32_e32 v41, 0x80000000, v41
	v_med3_u32 v96, v96, v95, v17
	v_max_u32_e32 v98, v97, v21
	v_or_b32_e32 v28, 0xde, v28
	v_bitop3_b32 v12, v41, s27, v12 bitop3:0x48
	v_add_f32_e32 v41, v4, v13
	v_med3_u32 v97, v97, v96, v21
	v_max_u32_e32 v99, v98, v28
	v_or_b32_e32 v29, 0xdd, v29
	v_ashrrev_i32_e32 v101, 31, v41
	v_med3_u32 v98, v98, v97, v28
	v_max_u32_e32 v100, v99, v29
	v_or_b32_e32 v30, 0xdc, v30
	v_or_b32_e32 v101, 0x80000000, v101
	v_med3_u32 v99, v99, v98, v29
	v_or_b32_e32 v18, 0xdb, v18
	v_bitop3_b32 v41, v101, s27, v41 bitop3:0x48
	v_max_u32_e32 v101, v100, v30
	v_med3_u32 v100, v100, v99, v30
	v_or_b32_e32 v32, 0xcf, v32
	v_max_u32_e32 v102, v101, v18
	v_med3_u32 v101, v101, v100, v18
	v_or_b32_e32 v33, 0xce, v33
	v_max_u32_e32 v103, v102, v32
	v_med3_u32 v102, v102, v101, v32
	v_or_b32_e32 v34, 0xcd, v34
	v_max_u32_e32 v104, v103, v33
	v_med3_u32 v103, v103, v102, v33
	v_or_b32_e32 v15, 0xcc, v15
	v_max_u32_e32 v105, v104, v34
	v_med3_u32 v104, v104, v103, v34
	v_or_b32_e32 v35, 0xbf, v35
	v_add_f32_e32 v5, v5, v13
	v_max_u32_e32 v106, v105, v15
	v_med3_u32 v105, v105, v104, v15
	v_or_b32_e32 v36, 0xbe, v36
	v_ashrrev_i32_e32 v13, 31, v5
	v_max_u32_e32 v107, v106, v35
	v_med3_u32 v106, v106, v105, v35
	v_or_b32_e32 v14, 0xbd, v14
	v_or_b32_e32 v13, 0x80000000, v13
	v_max_u32_e32 v108, v107, v36
	v_add_f32_e32 v10, v4, v10
	v_med3_u32 v107, v107, v106, v36
	v_or_b32_e32 v38, 0xaf, v38
	v_bitop3_b32 v5, v13, s27, v5 bitop3:0x48
	v_max_u32_e32 v109, v108, v14
	v_ashrrev_i32_e32 v13, 31, v10
	v_med3_u32 v108, v108, v107, v14
	v_or_b32_e32 v39, 0xae, v39
	v_max_u32_e32 v110, v109, v38
	v_or_b32_e32 v13, 0x80000000, v13
	v_add_f32_e32 v11, v4, v11
	v_med3_u32 v109, v109, v108, v38
	v_or_b32_e32 v40, 0x9f, v40
	v_max_u32_e32 v111, v110, v39
	v_bitop3_b32 v10, v13, s27, v10 bitop3:0x48
	v_ashrrev_i32_e32 v13, 31, v11
	v_med3_u32 v110, v110, v109, v39
	v_or_b32_e32 v12, 0x9e, v12
	v_max_u32_e32 v112, v111, v40
	v_or_b32_e32 v13, 0x80000000, v13
	v_add_f32_e32 v8, v4, v8
	v_med3_u32 v111, v111, v110, v40
	v_or_b32_e32 v41, 0x8f, v41
	v_max_u32_e32 v113, v112, v12
	v_bitop3_b32 v11, v13, s27, v11 bitop3:0x48
	v_ashrrev_i32_e32 v13, 31, v8
	v_med3_u32 v112, v112, v111, v12
	v_or_b32_e32 v5, 0x8e, v5
	v_max_u32_e32 v114, v113, v41
	v_or_b32_e32 v13, 0x80000000, v13
	v_add_f32_e32 v9, v4, v9
	v_med3_u32 v113, v113, v112, v41
	v_max_u32_e32 v115, v114, v5
	v_or_b32_e32 v10, 0x7f, v10
; #define TOPK_INSERT(keys, x) { _Pragma("unroll") for (int _j = 15; _j >= 1; --_j) keys[_j] = med3u(keys[_j - 1], keys[_j], x); keys[0] = max(keys[0], x); }
; DI unsigned f2ord(float v) { unsigned u = __float_as_uint(v); return u ^ ((unsigned)((int)u >> 31) | 0x80000000u); }
; DI void phase8(const Params& p, char* smem) {
;     ...
;       for (int i = 0; i < 16; ++i)
; #pragma unroll
;         for (int j = 0; j < 16; ++j)
;           if ((i + 1) * (j + 1) <= 16) {
;             unsigned x = (f2ord(a[i] + bq[j]) & 0xFFFFFF00u) | (unsigned)(255 - (i * 16 + j));
;             TOPK_INSERT(keys, x);
;           }
	v_bitop3_b32 v8, v13, s27, v8 bitop3:0x48
	v_ashrrev_i32_e32 v13, 31, v9
	v_med3_u32 v114, v114, v113, v5
	v_max_u32_e32 v116, v115, v10
	v_or_b32_e32 v11, 0x6f, v11
	v_or_b32_e32 v13, 0x80000000, v13
	v_add_f32_e32 v6, v4, v6
	v_med3_u32 v115, v115, v114, v10
	v_max_u32_e32 v117, v116, v11
	v_or_b32_e32 v8, 0x5f, v8
	v_bitop3_b32 v9, v13, s27, v9 bitop3:0x48
	v_ashrrev_i32_e32 v13, 31, v6
	v_add_f32_e32 v7, v4, v7
	v_med3_u32 v116, v116, v115, v11
	v_max_u32_e32 v118, v117, v8
	v_or_b32_e32 v9, 0x4f, v9
	v_bitop3_b32 v6, v13, v6, s24 bitop3:0x36
	v_ashrrev_i32_e32 v13, 31, v7
	v_add_f32_e32 v2, v4, v2
	v_med3_u32 v117, v117, v116, v8
	v_max_u32_e32 v119, v118, v9
	v_and_or_b32 v6, v6, s27, 63
	v_bitop3_b32 v7, v13, v7, s24 bitop3:0x36
	v_ashrrev_i32_e32 v13, 31, v2
	v_med3_u32 v118, v118, v117, v9
	v_max_u32_e32 v120, v119, v6
	v_and_or_b32 v7, v7, s27, 47
	v_bitop3_b32 v2, v13, v2, s24 bitop3:0x36
	v_med3_u32 v119, v119, v118, v6
	v_max_u32_e32 v121, v120, v7
	v_and_or_b32 v13, v2, s27, 31
	v_med3_u32 v120, v120, v119, v7
	v_min_u32_e32 v49, v122, v49
	v_min_u32_e32 v46, v46, v51
	v_max_u32_e32 v2, v121, v13
	v_med3_u32 v44, v121, v120, v13
	v_max_u32_e32 v121, v49, v46
	v_med3_u32 v50, v50, v121, v53
	v_med3_u32 v52, v52, v50, v55
	v_med3_u32 v54, v54, v52, v57
	v_med3_u32 v56, v56, v54, v48
	v_med3_u32 v58, v58, v56, v47
	v_med3_u32 v59, v59, v58, v45
	v_med3_u32 v60, v60, v59, v43
	v_med3_u32 v61, v61, v60, v42
	v_med3_u32 v62, v62, v61, v37
	v_med3_u32 v63, v63, v62, v31
	v_med3_u32 v64, v64, v63, v27
	v_med3_u32 v65, v65, v64, v16
	v_med3_u32 v66, v66, v65, v22
	v_med3_u32 v89, v89, v66, v23
	v_med3_u32 v90, v90, v89, v24
	v_med3_u32 v91, v91, v90, v25
	v_med3_u32 v92, v92, v91, v26
	v_med3_u32 v93, v93, v92, v19
	v_med3_u32 v94, v94, v93, v20
	v_med3_u32 v95, v95, v94, v17
	v_med3_u32 v96, v96, v95, v21
	v_med3_u32 v97, v97, v96, v28
	v_med3_u32 v98, v98, v97, v29
	v_med3_u32 v99, v99, v98, v30
	v_med3_u32 v100, v100, v99, v18
	v_med3_u32 v101, v101, v100, v32
	v_med3_u32 v102, v102, v101, v33
	v_med3_u32 v103, v103, v102, v34
	v_med3_u32 v104, v104, v103, v15
	v_med3_u32 v105, v105, v104, v35
	v_med3_u32 v106, v106, v105, v36
	v_med3_u32 v107, v107, v106, v14
	v_med3_u32 v108, v108, v107, v38
	v_med3_u32 v109, v109, v108, v39
	v_med3_u32 v110, v110, v109, v40
	v_med3_u32 v111, v111, v110, v12
	v_med3_u32 v112, v112, v111, v41
	v_med3_u32 v113, v113, v112, v5
	v_med3_u32 v114, v114, v113, v10
	v_med3_u32 v115, v115, v114, v11
	v_med3_u32 v116, v116, v115, v8
	v_med3_u32 v117, v117, v116, v9
	v_med3_u32 v118, v118, v117, v6
	v_med3_u32 v119, v119, v118, v7
	v_min_u32_e32 v51, v49, v51
	v_min_u32_e32 v49, v121, v53
	v_med3_u32 v46, v120, v119, v13
	v_max_u32_e32 v120, v51, v49
	v_min_u32_e32 v51, v51, v53
	v_min_u32_e32 v53, v120, v55
	v_med3_u32 v50, v50, v120, v55
	v_max_u32_e32 v53, v51, v53
	v_med3_u32 v52, v52, v50, v57
	v_med3_u32 v50, v50, v53, v57
	v_min_u32_e32 v51, v51, v55
	v_min_u32_e32 v53, v53, v57
	v_max_u32_e32 v53, v51, v53
	v_med3_u32 v54, v54, v52, v48
	v_med3_u32 v52, v52, v50, v48
	v_med3_u32 v50, v50, v53, v48
	v_min_u32_e32 v51, v51, v57
	v_min_u32_e32 v53, v53, v48
	v_max_u32_e32 v53, v51, v53
	v_min_u32_e32 v48, v51, v48
	v_min_u32_e32 v51, v53, v47
	v_max_u32_e32 v51, v48, v51
	v_med3_u32 v56, v56, v54, v47
	v_med3_u32 v54, v54, v52, v47
	v_med3_u32 v52, v52, v50, v47
	v_med3_u32 v50, v50, v53, v47
	v_min_u32_e32 v47, v48, v47
	v_min_u32_e32 v48, v51, v45
	v_max_u32_e32 v48, v47, v48
	v_med3_u32 v58, v58, v56, v45
	v_med3_u32 v56, v56, v54, v45
	v_med3_u32 v54, v54, v52, v45
	v_med3_u32 v52, v52, v50, v45
	v_med3_u32 v50, v50, v51, v45
	v_min_u32_e32 v45, v47, v45
	v_min_u32_e32 v47, v48, v43
	v_max_u32_e32 v47, v45, v47
	v_med3_u32 v59, v59, v58, v43
	v_med3_u32 v58, v58, v56, v43
	v_med3_u32 v55, v56, v54, v43
	v_med3_u32 v54, v54, v52, v43
	v_med3_u32 v52, v52, v50, v43
	v_med3_u32 v50, v50, v48, v43
	v_min_u32_e32 v43, v45, v43
	v_min_u32_e32 v45, v47, v42
	v_max_u32_e32 v45, v43, v45
	v_med3_u32 v60, v60, v59, v42
	v_med3_u32 v59, v59, v58, v42
	v_med3_u32 v56, v58, v55, v42
	v_med3_u32 v55, v55, v54, v42
	v_med3_u32 v53, v54, v52, v42
	v_med3_u32 v51, v52, v50, v42
	v_med3_u32 v48, v50, v47, v42
	v_min_u32_e32 v42, v43, v42
	v_min_u32_e32 v43, v45, v37
	v_max_u32_e32 v43, v42, v43
	v_med3_u32 v61, v61, v60, v37
	v_med3_u32 v60, v60, v59, v37
	v_med3_u32 v58, v59, v56, v37
	v_med3_u32 v56, v56, v55, v37
	v_med3_u32 v54, v55, v53, v37
	v_med3_u32 v52, v53, v51, v37
	v_med3_u32 v50, v51, v48, v37
	v_med3_u32 v47, v48, v45, v37
	v_min_u32_e32 v37, v42, v37
	v_min_u32_e32 v42, v43, v31
	v_max_u32_e32 v42, v37, v42
	v_med3_u32 v62, v62, v61, v31
	v_med3_u32 v61, v61, v60, v31
	v_med3_u32 v59, v60, v58, v31
	v_med3_u32 v57, v58, v56, v31
	v_med3_u32 v55, v56, v54, v31
	v_med3_u32 v53, v54, v52, v31
	v_med3_u32 v51, v52, v50, v31
	v_med3_u32 v48, v50, v47, v31
	v_med3_u32 v45, v47, v43, v31
	v_min_u32_e32 v31, v37, v31
	v_min_u32_e32 v37, v42, v27
	v_max_u32_e32 v37, v31, v37
	v_med3_u32 v63, v63, v62, v27
	v_med3_u32 v62, v62, v61, v27
	v_med3_u32 v60, v61, v59, v27
	v_med3_u32 v58, v59, v57, v27
	v_med3_u32 v56, v57, v55, v27
	v_med3_u32 v54, v55, v53, v27
	v_med3_u32 v52, v53, v51, v27
	v_med3_u32 v50, v51, v48, v27
	v_med3_u32 v47, v48, v45, v27
	v_med3_u32 v43, v45, v42, v27
	v_min_u32_e32 v27, v31, v27
	v_min_u32_e32 v31, v37, v16
	v_med3_u32 v64, v64, v63, v16
	v_med3_u32 v63, v63, v62, v16
	v_med3_u32 v61, v62, v60, v16
	v_med3_u32 v59, v60, v58, v16
	v_med3_u32 v57, v58, v56, v16
	v_med3_u32 v55, v56, v54, v16
	v_med3_u32 v53, v54, v52, v16
	v_med3_u32 v51, v52, v50, v16
	v_med3_u32 v48, v50, v47, v16
; #define TOPK_INSERT(keys, x) { _Pragma("unroll") for (int _j = 15; _j >= 1; --_j) keys[_j] = med3u(keys[_j - 1], keys[_j], x); keys[0] = max(keys[0], x); }
; DI unsigned f2ord(float v) { unsigned u = __float_as_uint(v); return u ^ ((unsigned)((int)u >> 31) | 0x80000000u); }
; DI void phase8(const Params& p, char* smem) {
;     ...
;       for (int i = 0; i < 16; ++i)
; #pragma unroll
;         for (int j = 0; j < 16; ++j)
;           if ((i + 1) * (j + 1) <= 16) {
;             unsigned x = (f2ord(a[i] + bq[j]) & 0xFFFFFF00u) | (unsigned)(255 - (i * 16 + j));
;             TOPK_INSERT(keys, x);
;           }
	v_med3_u32 v45, v47, v43, v16
	v_med3_u32 v42, v43, v37, v16
	v_max_u32_e32 v31, v27, v31
	v_med3_u32 v65, v65, v64, v22
	v_med3_u32 v64, v64, v63, v22
	v_med3_u32 v62, v63, v61, v22
	v_med3_u32 v60, v61, v59, v22
	v_med3_u32 v58, v59, v57, v22
	v_med3_u32 v56, v57, v55, v22
	v_med3_u32 v54, v55, v53, v22
	v_med3_u32 v52, v53, v51, v22
	v_med3_u32 v50, v51, v48, v22
	v_med3_u32 v47, v48, v45, v22
	v_med3_u32 v43, v45, v42, v22
	v_med3_u32 v37, v42, v31, v22
	v_min_u32_e32 v16, v27, v16
	v_min_u32_e32 v22, v31, v22
	v_med3_u32 v66, v66, v65, v23
	v_max_u32_e32 v16, v16, v22
	v_med3_u32 v89, v89, v66, v24
	v_med3_u32 v65, v65, v64, v23
	v_med3_u32 v63, v64, v62, v23
	v_med3_u32 v61, v62, v60, v23
	v_med3_u32 v59, v60, v58, v23
	v_med3_u32 v57, v58, v56, v23
	v_med3_u32 v55, v56, v54, v23
	v_med3_u32 v53, v54, v52, v23
	v_med3_u32 v51, v52, v50, v23
	v_med3_u32 v48, v50, v47, v23
	v_med3_u32 v45, v47, v43, v23
	v_med3_u32 v42, v43, v37, v23
	v_med3_u32 v16, v37, v16, v23
	v_med3_u32 v90, v90, v89, v25
	v_med3_u32 v66, v66, v65, v24
	v_med3_u32 v64, v65, v63, v24
	v_med3_u32 v62, v63, v61, v24
	v_med3_u32 v60, v61, v59, v24
	v_med3_u32 v58, v59, v57, v24
	v_med3_u32 v56, v57, v55, v24
	v_med3_u32 v54, v55, v53, v24
	v_med3_u32 v52, v53, v51, v24
	v_med3_u32 v50, v51, v48, v24
	v_med3_u32 v47, v48, v45, v24
	v_med3_u32 v43, v45, v42, v24
	v_med3_u32 v16, v42, v16, v24
	v_med3_u32 v91, v91, v90, v26
	v_med3_u32 v89, v89, v66, v25
	v_med3_u32 v65, v66, v64, v25
	v_med3_u32 v63, v64, v62, v25
	v_med3_u32 v61, v62, v60, v25
	v_med3_u32 v59, v60, v58, v25
	v_med3_u32 v57, v58, v56, v25
	v_med3_u32 v55, v56, v54, v25
	v_med3_u32 v53, v54, v52, v25
	v_med3_u32 v51, v52, v50, v25
	v_med3_u32 v48, v50, v47, v25
	v_med3_u32 v45, v47, v43, v25
	v_med3_u32 v16, v43, v16, v25
	v_med3_u32 v92, v92, v91, v19
	v_med3_u32 v90, v90, v89, v26
	v_med3_u32 v66, v89, v65, v26
	v_med3_u32 v64, v65, v63, v26
	v_med3_u32 v62, v63, v61, v26
	v_med3_u32 v60, v61, v59, v26
	v_med3_u32 v58, v59, v57, v26
	v_med3_u32 v56, v57, v55, v26
	v_med3_u32 v54, v55, v53, v26
	v_med3_u32 v52, v53, v51, v26
	v_med3_u32 v50, v51, v48, v26
	v_med3_u32 v47, v48, v45, v26
	v_med3_u32 v16, v45, v16, v26
	v_med3_u32 v93, v93, v92, v20
	v_med3_u32 v91, v91, v90, v19
	v_med3_u32 v89, v90, v66, v19
	v_med3_u32 v65, v66, v64, v19
	v_med3_u32 v63, v64, v62, v19
	v_med3_u32 v61, v62, v60, v19
	v_med3_u32 v59, v60, v58, v19
	v_med3_u32 v57, v58, v56, v19
	v_med3_u32 v55, v56, v54, v19
	v_med3_u32 v53, v54, v52, v19
	v_med3_u32 v51, v52, v50, v19
	v_med3_u32 v48, v50, v47, v19
	v_med3_u32 v16, v47, v16, v19
	v_med3_u32 v94, v94, v93, v17
	v_med3_u32 v92, v92, v91, v20
	v_med3_u32 v90, v91, v89, v20
	v_med3_u32 v66, v89, v65, v20
	v_med3_u32 v64, v65, v63, v20
	v_med3_u32 v62, v63, v61, v20
	v_med3_u32 v60, v61, v59, v20
	v_med3_u32 v58, v59, v57, v20
	v_med3_u32 v56, v57, v55, v20
	v_med3_u32 v54, v55, v53, v20
	v_med3_u32 v52, v53, v51, v20
	v_med3_u32 v50, v51, v48, v20
	v_med3_u32 v16, v48, v16, v20
	v_med3_u32 v95, v95, v94, v21
	v_med3_u32 v93, v93, v92, v17
	v_med3_u32 v91, v92, v90, v17
	v_med3_u32 v89, v90, v66, v17
	v_med3_u32 v65, v66, v64, v17
	v_med3_u32 v63, v64, v62, v17
	v_med3_u32 v61, v62, v60, v17
	v_med3_u32 v59, v60, v58, v17
	v_med3_u32 v57, v58, v56, v17
	v_med3_u32 v55, v56, v54, v17
	v_med3_u32 v53, v54, v52, v17
	v_med3_u32 v51, v52, v50, v17
	v_med3_u32 v16, v50, v16, v17
	v_med3_u32 v96, v96, v95, v28
	v_med3_u32 v94, v94, v93, v21
	v_med3_u32 v92, v93, v91, v21
	v_med3_u32 v90, v91, v89, v21
	v_med3_u32 v66, v89, v65, v21
	v_med3_u32 v64, v65, v63, v21
	v_med3_u32 v62, v63, v61, v21
	v_med3_u32 v60, v61, v59, v21
	v_med3_u32 v58, v59, v57, v21
	v_med3_u32 v56, v57, v55, v21
	v_med3_u32 v54, v55, v53, v21
	v_med3_u32 v52, v53, v51, v21
	v_med3_u32 v16, v51, v16, v21
	v_med3_u32 v97, v97, v96, v29
	v_med3_u32 v95, v95, v94, v28
	v_med3_u32 v93, v94, v92, v28
	v_med3_u32 v91, v92, v90, v28
	v_med3_u32 v89, v90, v66, v28
	v_med3_u32 v65, v66, v64, v28
	v_med3_u32 v63, v64, v62, v28
	v_med3_u32 v61, v62, v60, v28
	v_med3_u32 v59, v60, v58, v28
	v_med3_u32 v57, v58, v56, v28
	v_med3_u32 v55, v56, v54, v28
	v_med3_u32 v53, v54, v52, v28
	v_med3_u32 v16, v52, v16, v28
	v_med3_u32 v98, v98, v97, v30
	v_med3_u32 v96, v96, v95, v29
	v_med3_u32 v94, v95, v93, v29
	v_med3_u32 v92, v93, v91, v29
	v_med3_u32 v90, v91, v89, v29
	v_med3_u32 v66, v89, v65, v29
	v_med3_u32 v64, v65, v63, v29
	v_med3_u32 v62, v63, v61, v29
	v_med3_u32 v60, v61, v59, v29
	v_med3_u32 v58, v59, v57, v29
	v_med3_u32 v56, v57, v55, v29
	v_med3_u32 v54, v55, v53, v29
	v_med3_u32 v16, v53, v16, v29
	v_med3_u32 v99, v99, v98, v18
	v_med3_u32 v97, v97, v96, v30
	v_med3_u32 v95, v96, v94, v30
	v_med3_u32 v93, v94, v92, v30
	v_med3_u32 v91, v92, v90, v30
	v_med3_u32 v89, v90, v66, v30
	v_med3_u32 v65, v66, v64, v30
	v_med3_u32 v63, v64, v62, v30
	v_med3_u32 v61, v62, v60, v30
	v_med3_u32 v59, v60, v58, v30
	v_med3_u32 v57, v58, v56, v30
	v_med3_u32 v55, v56, v54, v30
	v_med3_u32 v16, v54, v16, v30
	v_med3_u32 v100, v100, v99, v32
	v_med3_u32 v98, v98, v97, v18
	v_med3_u32 v96, v97, v95, v18
	v_med3_u32 v94, v95, v93, v18
	v_med3_u32 v92, v93, v91, v18
	v_med3_u32 v90, v91, v89, v18
	v_med3_u32 v66, v89, v65, v18
	v_med3_u32 v64, v65, v63, v18
	v_med3_u32 v62, v63, v61, v18
	v_med3_u32 v60, v61, v59, v18
	v_med3_u32 v58, v59, v57, v18
	v_med3_u32 v56, v57, v55, v18
	v_med3_u32 v16, v55, v16, v18
	v_med3_u32 v101, v101, v100, v33
	v_med3_u32 v99, v99, v98, v32
	v_med3_u32 v97, v98, v96, v32
	v_med3_u32 v95, v96, v94, v32
	v_med3_u32 v93, v94, v92, v32
	v_med3_u32 v91, v92, v90, v32
	v_med3_u32 v89, v90, v66, v32
; #define TOPK_INSERT(keys, x) { _Pragma("unroll") for (int _j = 15; _j >= 1; --_j) keys[_j] = med3u(keys[_j - 1], keys[_j], x); keys[0] = max(keys[0], x); }
; DI unsigned f2ord(float v) { unsigned u = __float_as_uint(v); return u ^ ((unsigned)((int)u >> 31) | 0x80000000u); }
; DI void phase8(const Params& p, char* smem) {
;     ...
;       for (int i = 0; i < 16; ++i)
; #pragma unroll
;         for (int j = 0; j < 16; ++j)
;           if ((i + 1) * (j + 1) <= 16) {
;             unsigned x = (f2ord(a[i] + bq[j]) & 0xFFFFFF00u) | (unsigned)(255 - (i * 16 + j));
;             TOPK_INSERT(keys, x);
;           }
	v_med3_u32 v65, v66, v64, v32
	v_med3_u32 v63, v64, v62, v32
	v_med3_u32 v61, v62, v60, v32
	v_med3_u32 v59, v60, v58, v32
	v_med3_u32 v57, v58, v56, v32
	v_med3_u32 v16, v56, v16, v32
	v_med3_u32 v102, v102, v101, v34
	v_med3_u32 v100, v100, v99, v33
	v_med3_u32 v98, v99, v97, v33
	v_med3_u32 v96, v97, v95, v33
	v_med3_u32 v94, v95, v93, v33
	v_med3_u32 v92, v93, v91, v33
	v_med3_u32 v90, v91, v89, v33
	v_med3_u32 v66, v89, v65, v33
	v_med3_u32 v64, v65, v63, v33
	v_med3_u32 v62, v63, v61, v33
	v_med3_u32 v60, v61, v59, v33
	v_med3_u32 v58, v59, v57, v33
	v_med3_u32 v16, v57, v16, v33
	v_med3_u32 v103, v103, v102, v15
	v_med3_u32 v101, v101, v100, v34
	v_med3_u32 v99, v100, v98, v34
	v_med3_u32 v97, v98, v96, v34
	v_med3_u32 v95, v96, v94, v34
	v_med3_u32 v93, v94, v92, v34
	v_med3_u32 v91, v92, v90, v34
	v_med3_u32 v89, v90, v66, v34
	v_med3_u32 v65, v66, v64, v34
	v_med3_u32 v63, v64, v62, v34
	v_med3_u32 v61, v62, v60, v34
	v_med3_u32 v59, v60, v58, v34
	v_med3_u32 v16, v58, v16, v34
	v_med3_u32 v104, v104, v103, v35
	v_med3_u32 v102, v102, v101, v15
	v_med3_u32 v100, v101, v99, v15
	v_med3_u32 v98, v99, v97, v15
	v_med3_u32 v96, v97, v95, v15
	v_med3_u32 v94, v95, v93, v15
	v_med3_u32 v92, v93, v91, v15
	v_med3_u32 v90, v91, v89, v15
	v_med3_u32 v66, v89, v65, v15
	v_med3_u32 v64, v65, v63, v15
	v_med3_u32 v62, v63, v61, v15
	v_med3_u32 v60, v61, v59, v15
	v_med3_u32 v15, v59, v16, v15
	v_med3_u32 v105, v105, v104, v36
	v_med3_u32 v103, v103, v102, v35
	v_med3_u32 v101, v102, v100, v35
	v_med3_u32 v99, v100, v98, v35
	v_med3_u32 v97, v98, v96, v35
	v_med3_u32 v95, v96, v94, v35
	v_med3_u32 v93, v94, v92, v35
	v_med3_u32 v91, v92, v90, v35
	v_med3_u32 v89, v90, v66, v35
	v_med3_u32 v65, v66, v64, v35
	v_med3_u32 v63, v64, v62, v35
	v_med3_u32 v61, v62, v60, v35
	v_med3_u32 v15, v60, v15, v35
	v_med3_u32 v106, v106, v105, v14
	v_med3_u32 v104, v104, v103, v36
	v_med3_u32 v102, v103, v101, v36
	v_med3_u32 v100, v101, v99, v36
	v_med3_u32 v98, v99, v97, v36
	v_med3_u32 v96, v97, v95, v36
	v_med3_u32 v94, v95, v93, v36
	v_med3_u32 v92, v93, v91, v36
	v_med3_u32 v90, v91, v89, v36
	v_med3_u32 v66, v89, v65, v36
	v_med3_u32 v64, v65, v63, v36
	v_med3_u32 v62, v63, v61, v36
	v_med3_u32 v15, v61, v15, v36
	v_med3_u32 v107, v107, v106, v38
	v_med3_u32 v105, v105, v104, v14
	v_med3_u32 v103, v104, v102, v14
	v_med3_u32 v101, v102, v100, v14
	v_med3_u32 v99, v100, v98, v14
	v_med3_u32 v97, v98, v96, v14
	v_med3_u32 v95, v96, v94, v14
	v_med3_u32 v93, v94, v92, v14
	v_med3_u32 v91, v92, v90, v14
	v_med3_u32 v89, v90, v66, v14
	v_med3_u32 v65, v66, v64, v14
	v_med3_u32 v63, v64, v62, v14
	v_med3_u32 v14, v62, v15, v14
	v_med3_u32 v108, v108, v107, v39
	v_med3_u32 v106, v106, v105, v38
	v_med3_u32 v104, v105, v103, v38
	v_med3_u32 v102, v103, v101, v38
	v_med3_u32 v100, v101, v99, v38
	v_med3_u32 v98, v99, v97, v38
	v_med3_u32 v96, v97, v95, v38
	v_med3_u32 v94, v95, v93, v38
	v_med3_u32 v92, v93, v91, v38
	v_med3_u32 v90, v91, v89, v38
	v_med3_u32 v66, v89, v65, v38
	v_med3_u32 v64, v65, v63, v38
	v_med3_u32 v14, v63, v14, v38
	v_med3_u32 v109, v109, v108, v40
	v_med3_u32 v107, v107, v106, v39
	v_med3_u32 v105, v106, v104, v39
	v_med3_u32 v103, v104, v102, v39
	v_med3_u32 v101, v102, v100, v39
	v_med3_u32 v99, v100, v98, v39
	v_med3_u32 v97, v98, v96, v39
	v_med3_u32 v95, v96, v94, v39
	v_med3_u32 v93, v94, v92, v39
	v_med3_u32 v91, v92, v90, v39
	v_med3_u32 v89, v90, v66, v39
	v_med3_u32 v65, v66, v64, v39
	v_med3_u32 v14, v64, v14, v39
	v_med3_u32 v110, v110, v109, v12
	v_med3_u32 v108, v108, v107, v40
	v_med3_u32 v106, v107, v105, v40
	v_med3_u32 v104, v105, v103, v40
	v_med3_u32 v102, v103, v101, v40
	v_med3_u32 v100, v101, v99, v40
	v_med3_u32 v98, v99, v97, v40
	v_med3_u32 v96, v97, v95, v40
	v_med3_u32 v94, v95, v93, v40
	v_med3_u32 v92, v93, v91, v40
	v_med3_u32 v90, v91, v89, v40
	v_med3_u32 v66, v89, v65, v40
	v_med3_u32 v14, v65, v14, v40
	v_med3_u32 v111, v111, v110, v41
	v_med3_u32 v109, v109, v108, v12
	v_med3_u32 v107, v108, v106, v12
	v_med3_u32 v105, v106, v104, v12
	v_med3_u32 v103, v104, v102, v12
	v_med3_u32 v101, v102, v100, v12
	v_med3_u32 v99, v100, v98, v12
	v_med3_u32 v97, v98, v96, v12
	v_med3_u32 v95, v96, v94, v12
	v_med3_u32 v93, v94, v92, v12
	v_med3_u32 v91, v92, v90, v12
	v_med3_u32 v89, v90, v66, v12
	v_med3_u32 v12, v66, v14, v12
	v_med3_u32 v112, v112, v111, v5
	v_med3_u32 v110, v110, v109, v41
	v_med3_u32 v108, v109, v107, v41
	v_med3_u32 v106, v107, v105, v41
	v_med3_u32 v104, v105, v103, v41
	v_med3_u32 v102, v103, v101, v41
	v_med3_u32 v100, v101, v99, v41
	v_med3_u32 v98, v99, v97, v41
	v_med3_u32 v96, v97, v95, v41
	v_med3_u32 v94, v95, v93, v41
	v_med3_u32 v92, v93, v91, v41
	v_med3_u32 v90, v91, v89, v41
	v_med3_u32 v12, v89, v12, v41
	v_med3_u32 v113, v113, v112, v10
	v_med3_u32 v111, v111, v110, v5
	v_med3_u32 v109, v110, v108, v5
	v_med3_u32 v107, v108, v106, v5
	v_med3_u32 v105, v106, v104, v5
	v_med3_u32 v103, v104, v102, v5
	v_med3_u32 v101, v102, v100, v5
	v_med3_u32 v99, v100, v98, v5
	v_med3_u32 v97, v98, v96, v5
	v_med3_u32 v95, v96, v94, v5
	v_med3_u32 v93, v94, v92, v5
	v_med3_u32 v91, v92, v90, v5
	v_med3_u32 v5, v90, v12, v5
	v_med3_u32 v114, v114, v113, v11
	v_med3_u32 v112, v112, v111, v10
	v_med3_u32 v110, v111, v109, v10
	v_med3_u32 v108, v109, v107, v10
	v_med3_u32 v106, v107, v105, v10
	v_med3_u32 v104, v105, v103, v10
	v_med3_u32 v102, v103, v101, v10
	v_med3_u32 v100, v101, v99, v10
	v_med3_u32 v98, v99, v97, v10
	v_med3_u32 v96, v97, v95, v10
	v_med3_u32 v94, v95, v93, v10
	v_med3_u32 v92, v93, v91, v10
	v_med3_u32 v5, v91, v5, v10
	v_med3_u32 v115, v115, v114, v8
; DI unsigned f2ord(float v) { unsigned u = __float_as_uint(v); return u ^ ((unsigned)((int)u >> 31) | 0x80000000u); }
; #define TOPK_INSERT(keys, x) { _Pragma("unroll") for (int _j = 15; _j >= 1; --_j) keys[_j] = med3u(keys[_j - 1], keys[_j], x); keys[0] = max(keys[0], x); }
; DI void phase8(const Params& p, char* smem) {
;     ...
;       for (int i = 0; i < 16; ++i)
; #pragma unroll
;         for (int j = 0; j < 16; ++j)
;           if ((i + 1) * (j + 1) <= 16) {
;             unsigned x = (f2ord(a[i] + bq[j]) & 0xFFFFFF00u) | (unsigned)(255 - (i * 16 + j));
;             TOPK_INSERT(keys, x);
;           }
;       float bv[16]; int ex[16];
;       float mx = -1e30f;
; #pragma unroll
;       for (int q = 0; q < 16; ++q) {
;         const int flat = 255 - (int)(keys[q] & 255u), i = flat >> 4, j = flat & 15;
;         bv[q] = ra[i] + rb[j];
;         ex[q] = __float_as_int(ra[16 + i]) * 128 + __float_as_int(rb[16 + j]);
;         mx = fmaxf(mx, bv[q]);
	v_med3_u32 v113, v113, v112, v11
	v_med3_u32 v111, v112, v110, v11
	v_med3_u32 v109, v110, v108, v11
	v_med3_u32 v107, v108, v106, v11
	v_med3_u32 v105, v106, v104, v11
	v_med3_u32 v103, v104, v102, v11
	v_med3_u32 v101, v102, v100, v11
	v_med3_u32 v99, v100, v98, v11
	v_med3_u32 v97, v98, v96, v11
	v_med3_u32 v95, v96, v94, v11
	v_med3_u32 v93, v94, v92, v11
	v_med3_u32 v5, v92, v5, v11
	v_med3_u32 v116, v116, v115, v9
	v_med3_u32 v114, v114, v113, v8
	v_med3_u32 v112, v113, v111, v8
	v_med3_u32 v110, v111, v109, v8
	v_med3_u32 v108, v109, v107, v8
	v_med3_u32 v106, v107, v105, v8
	v_med3_u32 v104, v105, v103, v8
	v_med3_u32 v102, v103, v101, v8
	v_med3_u32 v100, v101, v99, v8
	v_med3_u32 v98, v99, v97, v8
	v_med3_u32 v96, v97, v95, v8
	v_med3_u32 v94, v95, v93, v8
	v_med3_u32 v5, v93, v5, v8
	v_add_f32_e32 v3, v4, v3
	v_med3_u32 v117, v117, v116, v6
	v_med3_u32 v115, v115, v114, v9
	v_med3_u32 v113, v114, v112, v9
	v_med3_u32 v111, v112, v110, v9
	v_med3_u32 v109, v110, v108, v9
	v_med3_u32 v107, v108, v106, v9
	v_med3_u32 v105, v106, v104, v9
	v_med3_u32 v103, v104, v102, v9
	v_med3_u32 v101, v102, v100, v9
	v_med3_u32 v99, v100, v98, v9
	v_med3_u32 v97, v98, v96, v9
	v_med3_u32 v95, v96, v94, v9
	v_med3_u32 v5, v94, v5, v9
	v_ashrrev_i32_e32 v4, 31, v3
	v_med3_u32 v118, v118, v117, v7
	v_med3_u32 v116, v116, v115, v6
	v_med3_u32 v114, v115, v113, v6
	v_med3_u32 v112, v113, v111, v6
	v_med3_u32 v110, v111, v109, v6
	v_med3_u32 v108, v109, v107, v6
	v_med3_u32 v106, v107, v105, v6
	v_med3_u32 v104, v105, v103, v6
	v_med3_u32 v102, v103, v101, v6
	v_med3_u32 v100, v101, v99, v6
	v_med3_u32 v98, v99, v97, v6
	v_med3_u32 v96, v97, v95, v6
	v_med3_u32 v5, v95, v5, v6
	v_bitop3_b32 v3, v4, v3, s24 bitop3:0x36
	v_med3_u32 v49, v119, v118, v13
	v_med3_u32 v117, v117, v116, v7
	v_med3_u32 v115, v116, v114, v7
	v_med3_u32 v113, v114, v112, v7
	v_med3_u32 v111, v112, v110, v7
	v_med3_u32 v109, v110, v108, v7
	v_med3_u32 v107, v108, v106, v7
	v_med3_u32 v105, v106, v104, v7
	v_med3_u32 v103, v104, v102, v7
	v_med3_u32 v101, v102, v100, v7
	v_med3_u32 v99, v100, v98, v7
	v_med3_u32 v97, v98, v96, v7
	v_med3_u32 v5, v96, v5, v7
	v_and_or_b32 v3, v3, s27, 15
	v_med3_u32 v118, v118, v117, v13
	v_med3_u32 v116, v117, v115, v13
	v_med3_u32 v114, v115, v113, v13
	v_med3_u32 v112, v113, v111, v13
	v_med3_u32 v110, v111, v109, v13
	v_med3_u32 v108, v109, v107, v13
	v_med3_u32 v106, v107, v105, v13
	v_med3_u32 v104, v105, v103, v13
	v_med3_u32 v102, v103, v101, v13
	v_med3_u32 v100, v101, v99, v13
	v_med3_u32 v98, v99, v97, v13
	v_med3_u32 v5, v97, v5, v13
	v_med3_u32 v14, v46, v49, v3
	v_med3_u32 v10, v44, v46, v3
	v_med3_u32 v6, v2, v44, v3
	v_max_u32_e32 v2, v2, v3
	v_med3_u32 v62, v98, v5, v3
	v_med3_u32 v58, v100, v98, v3
	v_med3_u32 v54, v102, v100, v3
	v_med3_u32 v50, v104, v102, v3
	v_med3_u32 v47, v106, v104, v3
	v_med3_u32 v42, v108, v106, v3
	v_med3_u32 v38, v110, v108, v3
	v_med3_u32 v34, v112, v110, v3
	v_med3_u32 v30, v114, v112, v3
	v_med3_u32 v26, v116, v114, v3
	v_med3_u32 v22, v118, v116, v3
	v_med3_u32 v18, v49, v118, v3
	v_not_b32_e32 v15, v14
	v_not_b32_e32 v11, v10
	v_not_b32_e32 v7, v6
	v_not_b32_e32 v3, v2
	v_bitop3_b32 v4, v2, 15, v2 bitop3:0xc
	v_lshrrev_b32_e32 v2, 2, v3
	v_bitop3_b32 v8, v6, 15, v6 bitop3:0xc
	v_lshrrev_b32_e32 v6, 2, v7
	v_bitop3_b32 v12, v10, 15, v10 bitop3:0xc
	v_lshrrev_b32_e32 v10, 2, v11
	v_bitop3_b32 v16, v14, 15, v14 bitop3:0xc
	v_lshrrev_b32_e32 v14, 2, v15
	v_and_b32_e32 v2, 60, v2
	v_lshl_add_u32 v4, v4, 2, v78
	v_and_b32_e32 v6, 60, v6
	v_lshl_add_u32 v8, v8, 2, v78
	v_and_b32_e32 v10, 60, v10
	v_lshl_add_u32 v12, v12, 2, v78
	v_and_b32_e32 v14, 60, v14
	v_lshl_add_u32 v16, v16, 2, v78
	v_add_u32_e32 v2, v78, v2
	v_add_u32_e32 v4, 0x8000, v4
	v_add_u32_e32 v6, v78, v6
	v_add_u32_e32 v8, 0x8000, v8
	v_add_u32_e32 v10, v78, v10
	v_add_u32_e32 v12, 0x8000, v12
	v_add_u32_e32 v14, v78, v14
	v_add_u32_e32 v16, 0x8000, v16
	ds_read2_b32 v[2:3], v2 offset0:4 offset1:20
	ds_read2_b32 v[4:5], v4 offset0:68 offset1:84
	ds_read2_b32 v[6:7], v6 offset0:4 offset1:20
	ds_read2_b32 v[8:9], v8 offset0:68 offset1:84
	ds_read2_b32 v[10:11], v10 offset0:4 offset1:20
	ds_read2_b32 v[12:13], v12 offset0:68 offset1:84
	ds_read2_b32 v[14:15], v14 offset0:4 offset1:20
	ds_read2_b32 v[16:17], v16 offset0:68 offset1:84
	v_not_b32_e32 v19, v18
	s_waitcnt lgkmcnt(6)
	v_add_f32_e32 v2, v2, v4
	s_waitcnt lgkmcnt(4)
	v_add_f32_e32 v4, v6, v8
	s_waitcnt lgkmcnt(2)
	v_add_f32_e32 v8, v10, v12
	s_waitcnt lgkmcnt(0)
	v_add_f32_e32 v10, v14, v16
	v_bitop3_b32 v12, v18, 15, v18 bitop3:0xc
	v_lshrrev_b32_e32 v14, 2, v19
	v_and_b32_e32 v14, 60, v14
	v_lshl_add_u32 v12, v12, 2, v78
	v_not_b32_e32 v23, v22
	v_add_u32_e32 v14, v78, v14
	v_add_u32_e32 v12, 0x8000, v12
	ds_read2_b32 v[18:19], v14 offset0:4 offset1:20
	ds_read2_b32 v[20:21], v12 offset0:68 offset1:84
	v_bitop3_b32 v12, v22, 15, v22 bitop3:0xc
	v_lshrrev_b32_e32 v14, 2, v23
	v_and_b32_e32 v14, 60, v14
	v_lshl_add_u32 v12, v12, 2, v78
	v_not_b32_e32 v27, v26
	v_add_u32_e32 v14, v78, v14
	v_add_u32_e32 v12, 0x8000, v12
	ds_read2_b32 v[22:23], v14 offset0:4 offset1:20
	ds_read2_b32 v[24:25], v12 offset0:68 offset1:84
	v_bitop3_b32 v12, v26, 15, v26 bitop3:0xc
	v_lshrrev_b32_e32 v14, 2, v27
	v_and_b32_e32 v14, 60, v14
	v_lshl_add_u32 v12, v12, 2, v78
	v_not_b32_e32 v31, v30
	v_add_u32_e32 v14, v78, v14
	v_add_u32_e32 v12, 0x8000, v12
	ds_read2_b32 v[26:27], v14 offset0:4 offset1:20
	ds_read2_b32 v[28:29], v12 offset0:68 offset1:84
	v_bitop3_b32 v12, v30, 15, v30 bitop3:0xc
	v_lshrrev_b32_e32 v14, 2, v31
	v_and_b32_e32 v14, 60, v14
	v_lshl_add_u32 v12, v12, 2, v78
	v_add_u32_e32 v14, v78, v14
	v_add_u32_e32 v12, 0x8000, v12
	ds_read2_b32 v[30:31], v14 offset0:4 offset1:20
	ds_read2_b32 v[32:33], v12 offset0:68 offset1:84
	v_not_b32_e32 v35, v34
	s_waitcnt lgkmcnt(6)
; DI void phase8(const Params& p, char* smem) {
;     ...
; #pragma unroll
;       for (int q = 0; q < 16; ++q) {
;         const int flat = 255 - (int)(keys[q] & 255u), i = flat >> 4, j = flat & 15;
;         bv[q] = ra[i] + rb[j];
;         ex[q] = __float_as_int(ra[16 + i]) * 128 + __float_as_int(rb[16 + j]);
;         mx = fmaxf(mx, bv[q]);
;       }
	v_add_f32_e32 v12, v18, v20
	s_waitcnt lgkmcnt(4)
	v_add_f32_e32 v14, v22, v24
	v_bitop3_b32 v20, v34, 15, v34 bitop3:0xc
	v_lshrrev_b32_e32 v22, 2, v35
	v_not_b32_e32 v51, v50
	v_and_b32_e32 v22, 60, v22
	v_lshl_add_u32 v20, v20, 2, v78
	v_not_b32_e32 v39, v38
	s_waitcnt lgkmcnt(2)
	v_add_f32_e32 v16, v26, v28
	s_waitcnt lgkmcnt(0)
	v_add_f32_e32 v18, v30, v32
	v_add_u32_e32 v22, v78, v22
	v_add_u32_e32 v20, 0x8000, v20
	v_bitop3_b32 v28, v50, 15, v50 bitop3:0xc
	v_lshrrev_b32_e32 v30, 2, v51
	ds_read2_b32 v[34:35], v22 offset0:4 offset1:20
	ds_read2_b32 v[36:37], v20 offset0:68 offset1:84
	v_bitop3_b32 v20, v38, 15, v38 bitop3:0xc
	v_lshrrev_b32_e32 v22, 2, v39
	v_and_b32_e32 v30, 60, v30
	v_lshl_add_u32 v28, v28, 2, v78
	v_not_b32_e32 v55, v54
	v_and_b32_e32 v22, 60, v22
	v_lshl_add_u32 v20, v20, 2, v78
	v_add_u32_e32 v30, v78, v30
	v_add_u32_e32 v28, 0x8000, v28
	v_not_b32_e32 v43, v42
	v_add_u32_e32 v22, v78, v22
	v_add_u32_e32 v20, 0x8000, v20
	ds_read2_b32 v[50:51], v30 offset0:4 offset1:20
	ds_read2_b32 v[52:53], v28 offset0:68 offset1:84
	v_bitop3_b32 v28, v54, 15, v54 bitop3:0xc
	v_lshrrev_b32_e32 v30, 2, v55
	ds_read2_b32 v[38:39], v22 offset0:4 offset1:20
	ds_read2_b32 v[40:41], v20 offset0:68 offset1:84
	v_bitop3_b32 v20, v42, 15, v42 bitop3:0xc
	v_lshrrev_b32_e32 v22, 2, v43
	v_and_b32_e32 v30, 60, v30
	v_lshl_add_u32 v28, v28, 2, v78
	v_not_b32_e32 v59, v58
	v_and_b32_e32 v22, 60, v22
	v_lshl_add_u32 v20, v20, 2, v78
	v_add_u32_e32 v30, v78, v30
	v_add_u32_e32 v28, 0x8000, v28
	v_not_b32_e32 v48, v47
	v_add_u32_e32 v22, v78, v22
	v_add_u32_e32 v20, 0x8000, v20
	ds_read2_b32 v[54:55], v30 offset0:4 offset1:20
	ds_read2_b32 v[56:57], v28 offset0:68 offset1:84
	v_bitop3_b32 v28, v58, 15, v58 bitop3:0xc
	v_lshrrev_b32_e32 v30, 2, v59
	ds_read2_b32 v[42:43], v22 offset0:4 offset1:20
	ds_read2_b32 v[44:45], v20 offset0:68 offset1:84
	v_bitop3_b32 v20, v47, 15, v47 bitop3:0xc
	v_lshrrev_b32_e32 v22, 2, v48
	v_and_b32_e32 v30, 60, v30
	v_lshl_add_u32 v28, v28, 2, v78
	v_not_b32_e32 v63, v62
	v_and_b32_e32 v22, 60, v22
	v_lshl_add_u32 v20, v20, 2, v78
	v_add_u32_e32 v30, v78, v30
	v_add_u32_e32 v28, 0x8000, v28
	v_add_u32_e32 v22, v78, v22
	v_add_u32_e32 v20, 0x8000, v20
	ds_read2_b32 v[58:59], v30 offset0:4 offset1:20
	ds_read2_b32 v[60:61], v28 offset0:68 offset1:84
	v_bitop3_b32 v28, v62, 15, v62 bitop3:0xc
	v_lshrrev_b32_e32 v30, 2, v63
	ds_read2_b32 v[46:47], v22 offset0:4 offset1:20
	ds_read2_b32 v[48:49], v20 offset0:68 offset1:84
	v_and_b32_e32 v30, 60, v30
	v_lshl_add_u32 v28, v28, 2, v78
	v_max3_f32 v6, v2, s28, v4
	v_add_u32_e32 v30, v78, v30
	v_add_u32_e32 v28, 0x8000, v28
	v_max3_f32 v6, v6, v8, v10
	ds_read2_b32 v[62:63], v30 offset0:4 offset1:20
	ds_read2_b32 v[64:65], v28 offset0:68 offset1:84
	v_max3_f32 v6, v6, v12, v14
	v_max3_f32 v6, v6, v16, v18
	s_waitcnt lgkmcnt(14)
	v_add_f32_e32 v20, v34, v36
	s_waitcnt lgkmcnt(10)
	v_add_f32_e32 v22, v38, v40
	v_max3_f32 v6, v6, v20, v22
	s_waitcnt lgkmcnt(6)
	v_add_f32_e32 v24, v42, v44
	s_waitcnt lgkmcnt(2)
	v_add_f32_e32 v26, v46, v48
	v_max3_f32 v6, v6, v24, v26
	v_add_f32_e32 v28, v50, v52
	v_add_f32_e32 v30, v54, v56
	v_max3_f32 v6, v6, v28, v30
	v_add_f32_e32 v32, v58, v60
	s_waitcnt lgkmcnt(0)
; DI void phase8(const Params& p, char* smem) {
;     ...
;       float sum = 0.f;
; #pragma unroll
;       for (int q = 0; q < 16; ++q) { bv[q] = __expf(bv[q] - mx); sum += bv[q]; }
;       const float inv = 1.f / sum;
;       const size_t o = (size_t)(tile * 64 + tid) * 128 + h * 16;
; #pragma unroll
;       for (int q = 0; q < 16; q += 4) {
;         *(int4*)(IDS + o + q) = make_int4(ex[q], ex[q + 1], ex[q + 2], ex[q + 3]);
;         *(float4*)(GATE + o + q) = make_float4(bv[q] * inv, bv[q + 1] * inv, bv[q + 2] * inv, bv[q + 3] * inv);
;       }
	v_add_f32_e32 v34, v62, v64
	v_max3_f32 v6, v6, v32, v34
	v_sub_f32_e32 v2, v2, v6
	v_mul_f32_e32 v2, 0x3fb8aa3b, v2
	v_exp_f32_e32 v90, v2
	v_sub_f32_e32 v2, v4, v6
	v_sub_f32_e32 v4, v12, v6
	v_mul_f32_e32 v4, 0x3fb8aa3b, v4
	v_exp_f32_e32 v94, v4
	v_sub_f32_e32 v4, v14, v6
	v_mul_f32_e32 v4, 0x3fb8aa3b, v4
	v_exp_f32_e32 v95, v4
	v_sub_f32_e32 v4, v16, v6
	v_mul_f32_e32 v4, 0x3fb8aa3b, v4
	v_exp_f32_e32 v96, v4
	v_sub_f32_e32 v4, v18, v6
	v_mul_f32_e32 v2, 0x3fb8aa3b, v2
	v_mul_f32_e32 v4, 0x3fb8aa3b, v4
	v_exp_f32_e32 v91, v2
	v_sub_f32_e32 v2, v8, v6
	v_exp_f32_e32 v97, v4
	v_sub_f32_e32 v4, v20, v6
	v_mul_f32_e32 v2, 0x3fb8aa3b, v2
	v_mul_f32_e32 v4, 0x3fb8aa3b, v4
	v_exp_f32_e32 v92, v2
	v_sub_f32_e32 v2, v10, v6
	v_exp_f32_e32 v98, v4
	v_sub_f32_e32 v4, v22, v6
	v_mul_f32_e32 v2, 0x3fb8aa3b, v2
	v_mul_f32_e32 v4, 0x3fb8aa3b, v4
	v_exp_f32_e32 v93, v2
	v_exp_f32_e32 v99, v4
	v_sub_f32_e32 v4, v24, v6
	v_add_f32_e32 v2, 0, v90
	v_mul_f32_e32 v4, 0x3fb8aa3b, v4
	v_add_f32_e32 v2, v91, v2
	v_exp_f32_e32 v100, v4
	v_sub_f32_e32 v4, v26, v6
	v_add_f32_e32 v2, v92, v2
	v_mul_f32_e32 v4, 0x3fb8aa3b, v4
	v_add_f32_e32 v2, v93, v2
	v_exp_f32_e32 v101, v4
	v_sub_f32_e32 v4, v28, v6
	v_add_f32_e32 v2, v94, v2
	v_mul_f32_e32 v4, 0x3fb8aa3b, v4
	v_add_f32_e32 v2, v95, v2
	v_exp_f32_e32 v102, v4
	v_sub_f32_e32 v4, v30, v6
	v_add_f32_e32 v2, v96, v2
	v_mul_f32_e32 v4, 0x3fb8aa3b, v4
	v_add_f32_e32 v2, v97, v2
	v_exp_f32_e32 v103, v4
	v_sub_f32_e32 v4, v32, v6
	v_add_f32_e32 v2, v98, v2
	v_mul_f32_e32 v4, 0x3fb8aa3b, v4
	v_add_f32_e32 v2, v99, v2
	v_exp_f32_e32 v104, v4
	v_sub_f32_e32 v4, v34, v6
	v_add_f32_e32 v2, v100, v2
	v_mul_f32_e32 v4, 0x3fb8aa3b, v4
	v_add_f32_e32 v2, v101, v2
	v_exp_f32_e32 v105, v4
	v_add_f32_e32 v2, v102, v2
	v_add_f32_e32 v2, v103, v2
	v_add_f32_e32 v2, v104, v2
	v_add_f32_e32 v2, v105, v2
	v_div_scale_f32 v4, s[34:35], v2, v2, 1.0
	v_rcp_f32_e32 v6, v4
	v_subrev_u32_e32 v106, 0xc0, v0
	v_or_b32_e32 v106, s31, v106
	v_ashrrev_i32_e32 v107, 31, v106
	v_lshlrev_b64 v[106:107], 9, v[106:107]
	v_fma_f32 v8, -v4, v6, 1.0
	v_fmac_f32_e32 v6, v8, v6
	v_div_scale_f32 v8, vcc, 1.0, v2, 1.0
	v_mul_f32_e32 v10, v8, v6
	v_fma_f32 v12, -v4, v10, v8
	v_fmac_f32_e32 v10, v12, v6
	v_fma_f32 v4, -v4, v10, v8
	v_div_fmas_f32 v4, v4, v6, v10
	v_div_fixup_f32 v10, v4, v2, 1.0
	v_lshl_or_b32 v106, s30, 6, v106
	v_lshl_add_u64 v[108:109], s[10:11], 0, v[106:107]
	v_lshl_add_u64 v[106:107], s[14:15], 0, v[106:107]
	v_lshl_add_u32 v6, v3, 7, v5
	v_pk_mul_f32 v[2:3], v[90:91], v[10:11] op_sel_hi:[1,0]
	v_pk_mul_f32 v[4:5], v[92:93], v[10:11] op_sel_hi:[1,0]
	global_store_dwordx4 v[106:107], v[2:5], off
	v_lshl_add_u32 v7, v7, 7, v9
	v_lshl_add_u32 v9, v15, 7, v17
	v_lshl_add_u32 v3, v23, 7, v25
	v_lshl_add_u32 v2, v19, 7, v21
	v_lshl_add_u32 v5, v31, 7, v33
	v_lshl_add_u32 v4, v27, 7, v29
	global_store_dwordx4 v[108:109], v[2:5], off offset:16
	v_lshl_add_u32 v8, v11, 7, v13
	global_store_dwordx4 v[108:109], v[6:9], off
	v_pk_mul_f32 v[2:3], v[94:95], v[10:11] op_sel_hi:[1,0]
	v_pk_mul_f32 v[4:5], v[96:97], v[10:11] op_sel_hi:[1,0]
	global_store_dwordx4 v[106:107], v[2:5], off offset:16
	s_nop 1
	v_lshl_add_u32 v3, v39, 7, v41
	v_lshl_add_u32 v2, v35, 7, v37
	v_lshl_add_u32 v5, v47, 7, v49
	v_lshl_add_u32 v4, v43, 7, v45
	global_store_dwordx4 v[108:109], v[2:5], off offset:32
	s_nop 1
	v_pk_mul_f32 v[2:3], v[98:99], v[10:11] op_sel_hi:[1,0]
	v_pk_mul_f32 v[4:5], v[100:101], v[10:11] op_sel_hi:[1,0]
	global_store_dwordx4 v[106:107], v[2:5], off offset:32
	s_nop 1
	v_lshl_add_u32 v3, v55, 7, v57
	v_lshl_add_u32 v2, v51, 7, v53
	v_lshl_add_u32 v5, v63, 7, v65
	v_lshl_add_u32 v4, v59, 7, v61
	global_store_dwordx4 v[108:109], v[2:5], off offset:48
	s_nop 1
	v_pk_mul_f32 v[2:3], v[102:103], v[10:11] op_sel_hi:[1,0]
	v_pk_mul_f32 v[4:5], v[104:105], v[10:11] op_sel_hi:[1,0]
	global_store_dwordx4 v[106:107], v[2:5], off offset:48
	s_branch .LBB0_1050
